# fold table + gate sigmoid epilogue without the redundant canonicalize/clamp pair (u8 conversion clamps)
# baseline (speedup 1.0000x reference)
.LBB0_1363:
	s_and_b64 vcc, exec, s[4:5]
	s_cbranch_vccz .LBB0_1538
	v_mul_f32_e32 v128, 0xbfb8aa3b, v128
	v_exp_f32_e32 v128, v128
	v_mul_f32_e32 v129, 0xbfb8aa3b, v129
	v_exp_f32_e32 v129, v129
	v_mul_f32_e32 v130, 0xbfb8aa3b, v130
	v_exp_f32_e32 v130, v130
	v_add_f32_e32 v128, 1.0, v128
	v_rcp_f32_e32 v128, v128
	v_add_f32_e32 v129, 1.0, v129
	v_mul_f32_e32 v131, 0xbfb8aa3b, v131
	v_rcp_f32_e32 v129, v129
	v_add_f32_e32 v130, 1.0, v130
	v_exp_f32_e32 v131, v131
	v_rcp_f32_e32 v130, v130
	v_fma_f32 v128, v128, s29, -0.5
	v_cvt_pk_u8_f32 v128, v128, 0, 0
	v_fma_f32 v129, v129, s29, -0.5
	v_mul_f32_e32 v124, 0xbfb8aa3b, v124
	v_add_f32_e32 v131, 1.0, v131
	v_cvt_pk_u8_f32 v128, v129, 1, v128
	v_fma_f32 v129, v130, s29, -0.5
	v_exp_f32_e32 v130, v124
	v_mov_b32_e32 v124, v125
	v_rcp_f32_e32 v131, v131
	v_mul_f32_e32 v120, 0xbfb8aa3b, v120
	v_mul_f32_e32 v116, 0xbfb8aa3b, v116
	v_mul_f32_e32 v124, 0xbfb8aa3b, v124
	v_exp_f32_e32 v120, v120
	v_mul_f32_e32 v121, 0xbfb8aa3b, v121
	v_exp_f32_e32 v116, v116
	v_mul_f32_e32 v117, 0xbfb8aa3b, v117
	v_exp_f32_e32 v125, v124
	v_mul_f32_e32 v126, 0xbfb8aa3b, v126
	v_exp_f32_e32 v121, v121
	v_mul_f32_e32 v122, 0xbfb8aa3b, v122
	v_exp_f32_e32 v117, v117
	v_mul_f32_e32 v118, 0xbfb8aa3b, v118
	v_exp_f32_e32 v126, v126
	v_mul_f32_e32 v127, 0xbfb8aa3b, v127
	v_exp_f32_e32 v122, v122
	v_mul_f32_e32 v123, 0xbfb8aa3b, v123
	v_exp_f32_e32 v118, v118
	v_mul_f32_e32 v119, 0xbfb8aa3b, v119
	v_cvt_pk_u8_f32 v128, v129, 2, v128
	v_fma_f32 v129, v131, s29, -0.5
	v_exp_f32_e32 v127, v127
	v_exp_f32_e32 v123, v123
	v_exp_f32_e32 v119, v119
	v_cvt_pk_u8_f32 v124, v129, 3, v128
	v_add_f32_e32 v128, 1.0, v130
	v_add_f32_e32 v120, 1.0, v120
	v_add_f32_e32 v116, 1.0, v116
	v_rcp_f32_e32 v128, v128
	v_add_f32_e32 v125, 1.0, v125
	v_rcp_f32_e32 v120, v120
	v_add_f32_e32 v121, 1.0, v121
	v_rcp_f32_e32 v116, v116
	v_add_f32_e32 v117, 1.0, v117
	v_rcp_f32_e32 v125, v125
	v_add_f32_e32 v126, 1.0, v126
	v_rcp_f32_e32 v121, v121
	v_add_f32_e32 v122, 1.0, v122
	v_rcp_f32_e32 v117, v117
	v_add_f32_e32 v118, 1.0, v118
	v_rcp_f32_e32 v126, v126
	v_add_f32_e32 v127, 1.0, v127
	v_rcp_f32_e32 v122, v122
	v_add_f32_e32 v123, 1.0, v123
	v_rcp_f32_e32 v118, v118
	v_add_f32_e32 v119, 1.0, v119
	v_rcp_f32_e32 v127, v127
	v_rcp_f32_e32 v123, v123
	v_rcp_f32_e32 v119, v119
	s_add_i32 s67, s67, 0x7ffff500
	v_fma_f32 v128, v128, s29, -0.5
	v_fma_f32 v120, v120, s29, -0.5
	v_fma_f32 v116, v116, s29, -0.5
	s_and_b32 s4, s67, 0x7fffff00
	v_readlane_b32 s5, v255, 7
	v_cvt_pk_u8_f32 v128, v128, 0, 0
	v_fma_f32 v125, v125, s29, -0.5
	v_cvt_pk_u8_f32 v120, v120, 0, 0
	v_fma_f32 v121, v121, s29, -0.5
	v_cvt_pk_u8_f32 v116, v116, 0, 0
	v_fma_f32 v117, v117, s29, -0.5
	s_or_b32 s4, s4, s5
	v_cvt_pk_u8_f32 v125, v125, 1, v128
	v_fma_f32 v126, v126, s29, -0.5
	v_cvt_pk_u8_f32 v120, v121, 1, v120
	v_fma_f32 v121, v122, s29, -0.5
	v_cvt_pk_u8_f32 v116, v117, 1, v116
	v_fma_f32 v117, v118, s29, -0.5
	v_lshl_add_u32 v2, v226, 4, s4
	v_cvt_pk_u8_f32 v125, v126, 2, v125
	v_fma_f32 v126, v127, s29, -0.5
	v_cvt_pk_u8_f32 v120, v121, 2, v120
	v_fma_f32 v121, v123, s29, -0.5
	v_cvt_pk_u8_f32 v116, v117, 2, v116
	v_fma_f32 v117, v119, s29, -0.5
	s_movk_i32 s20, 0xc00
	v_cvt_pk_u8_f32 v125, v126, 3, v125
	v_cvt_pk_u8_f32 v126, v121, 3, v120
	v_cvt_pk_u8_f32 v127, v117, 3, v116
	v_mad_u64_u32 v[116:117], s[4:5], v225, s20, v[2:3]
	global_store_dwordx4 v116, v[124:127], s[72:73]
	v_mul_f32_e32 v112, 0xbfb8aa3b, v112
	v_exp_f32_e32 v112, v112
	v_mul_f32_e32 v113, 0xbfb8aa3b, v113
	v_exp_f32_e32 v113, v113
	v_mul_f32_e32 v114, 0xbfb8aa3b, v114
	v_exp_f32_e32 v114, v114
	v_add_f32_e32 v112, 1.0, v112
	v_rcp_f32_e32 v112, v112
	v_add_f32_e32 v113, 1.0, v113
	v_mul_f32_e32 v115, 0xbfb8aa3b, v115
	v_rcp_f32_e32 v113, v113
	v_add_f32_e32 v114, 1.0, v114
	v_exp_f32_e32 v115, v115
	v_rcp_f32_e32 v114, v114
	v_fma_f32 v112, v112, s29, -0.5
	v_cvt_pk_u8_f32 v112, v112, 0, 0
	v_fma_f32 v113, v113, s29, -0.5
	v_mul_f32_e32 v108, 0xbfb8aa3b, v108
	v_add_f32_e32 v115, 1.0, v115
	v_cvt_pk_u8_f32 v112, v113, 1, v112
	v_fma_f32 v113, v114, s29, -0.5
	v_exp_f32_e32 v114, v108
	v_mov_b32_e32 v108, v109
	v_rcp_f32_e32 v115, v115
	v_mul_f32_e32 v104, 0xbfb8aa3b, v104
	v_mul_f32_e32 v100, 0xbfb8aa3b, v100
	v_mul_f32_e32 v108, 0xbfb8aa3b, v108
	v_exp_f32_e32 v104, v104
	v_mul_f32_e32 v105, 0xbfb8aa3b, v105
	v_exp_f32_e32 v100, v100
	v_mul_f32_e32 v101, 0xbfb8aa3b, v101
	v_exp_f32_e32 v109, v108
	v_mul_f32_e32 v110, 0xbfb8aa3b, v110
	v_exp_f32_e32 v105, v105
	v_mul_f32_e32 v106, 0xbfb8aa3b, v106
	v_exp_f32_e32 v101, v101
	v_mul_f32_e32 v102, 0xbfb8aa3b, v102
	v_exp_f32_e32 v110, v110
	v_mul_f32_e32 v111, 0xbfb8aa3b, v111
	v_exp_f32_e32 v106, v106
	v_mul_f32_e32 v107, 0xbfb8aa3b, v107
	v_exp_f32_e32 v102, v102
	v_mul_f32_e32 v103, 0xbfb8aa3b, v103
	v_cvt_pk_u8_f32 v112, v113, 2, v112
	v_fma_f32 v113, v115, s29, -0.5
	v_exp_f32_e32 v111, v111
	v_exp_f32_e32 v107, v107
	v_exp_f32_e32 v103, v103
	v_cvt_pk_u8_f32 v108, v113, 3, v112
	v_add_f32_e32 v112, 1.0, v114
	v_add_f32_e32 v104, 1.0, v104
	v_add_f32_e32 v100, 1.0, v100
	v_rcp_f32_e32 v112, v112
	v_add_f32_e32 v109, 1.0, v109
	v_rcp_f32_e32 v104, v104
	v_add_f32_e32 v105, 1.0, v105
	v_rcp_f32_e32 v100, v100
	v_add_f32_e32 v101, 1.0, v101
	v_rcp_f32_e32 v109, v109
	v_add_f32_e32 v110, 1.0, v110
	v_rcp_f32_e32 v105, v105
	v_add_f32_e32 v106, 1.0, v106
	v_rcp_f32_e32 v101, v101
	v_add_f32_e32 v102, 1.0, v102
	v_rcp_f32_e32 v110, v110
	v_add_f32_e32 v111, 1.0, v111
	v_rcp_f32_e32 v106, v106
	v_add_f32_e32 v107, 1.0, v107
	v_rcp_f32_e32 v102, v102
	v_add_f32_e32 v103, 1.0, v103
	v_rcp_f32_e32 v111, v111
	v_rcp_f32_e32 v107, v107
	v_rcp_f32_e32 v103, v103
	v_fma_f32 v112, v112, s29, -0.5
	v_fma_f32 v104, v104, s29, -0.5
	v_fma_f32 v100, v100, s29, -0.5
	v_cvt_pk_u8_f32 v112, v112, 0, 0
	v_fma_f32 v109, v109, s29, -0.5
	v_cvt_pk_u8_f32 v104, v104, 0, 0
	v_fma_f32 v105, v105, s29, -0.5
	v_cvt_pk_u8_f32 v100, v100, 0, 0
	v_fma_f32 v101, v101, s29, -0.5
	v_cvt_pk_u8_f32 v109, v109, 1, v112
	v_fma_f32 v110, v110, s29, -0.5
	v_cvt_pk_u8_f32 v104, v105, 1, v104
	v_fma_f32 v105, v106, s29, -0.5
	v_cvt_pk_u8_f32 v100, v101, 1, v100
	v_fma_f32 v101, v102, s29, -0.5
	v_cvt_pk_u8_f32 v109, v110, 2, v109
	v_fma_f32 v110, v111, s29, -0.5
	v_cvt_pk_u8_f32 v104, v105, 2, v104
	v_fma_f32 v105, v107, s29, -0.5
	v_cvt_pk_u8_f32 v100, v101, 2, v100
	v_fma_f32 v101, v103, s29, -0.5
	v_cvt_pk_u8_f32 v109, v110, 3, v109
	v_cvt_pk_u8_f32 v110, v105, 3, v104
	v_cvt_pk_u8_f32 v111, v101, 3, v100
	v_mad_u64_u32 v[100:101], s[4:5], v224, s20, v[2:3]
	global_store_dwordx4 v100, v[108:111], s[72:73]
	v_mul_f32_e32 v96, 0xbfb8aa3b, v96
	v_exp_f32_e32 v96, v96
	v_mul_f32_e32 v97, 0xbfb8aa3b, v97
	v_exp_f32_e32 v97, v97
	v_mul_f32_e32 v98, 0xbfb8aa3b, v98
	v_exp_f32_e32 v98, v98
	v_add_f32_e32 v96, 1.0, v96
	v_rcp_f32_e32 v96, v96
	v_add_f32_e32 v97, 1.0, v97
	v_mul_f32_e32 v99, 0xbfb8aa3b, v99
	v_rcp_f32_e32 v97, v97
	v_add_f32_e32 v98, 1.0, v98
	v_exp_f32_e32 v99, v99
	v_rcp_f32_e32 v98, v98
	v_fma_f32 v96, v96, s29, -0.5
	v_cvt_pk_u8_f32 v96, v96, 0, 0
	v_fma_f32 v97, v97, s29, -0.5
	v_mul_f32_e32 v92, 0xbfb8aa3b, v92
	v_add_f32_e32 v99, 1.0, v99
	v_cvt_pk_u8_f32 v96, v97, 1, v96
	v_fma_f32 v97, v98, s29, -0.5
	v_exp_f32_e32 v98, v92
	v_mov_b32_e32 v92, v93
	v_rcp_f32_e32 v99, v99
	v_mul_f32_e32 v88, 0xbfb8aa3b, v88
	v_mul_f32_e32 v84, 0xbfb8aa3b, v84
	v_mul_f32_e32 v92, 0xbfb8aa3b, v92
	v_exp_f32_e32 v88, v88
	v_mul_f32_e32 v89, 0xbfb8aa3b, v89
	v_exp_f32_e32 v84, v84
	v_mul_f32_e32 v85, 0xbfb8aa3b, v85
	v_exp_f32_e32 v93, v92
	v_mul_f32_e32 v94, 0xbfb8aa3b, v94
	v_exp_f32_e32 v89, v89
	v_mul_f32_e32 v90, 0xbfb8aa3b, v90
	v_exp_f32_e32 v85, v85
	v_mul_f32_e32 v86, 0xbfb8aa3b, v86
	v_exp_f32_e32 v94, v94
	v_mul_f32_e32 v95, 0xbfb8aa3b, v95
	v_exp_f32_e32 v90, v90
	v_mul_f32_e32 v91, 0xbfb8aa3b, v91
	v_exp_f32_e32 v86, v86
	v_mul_f32_e32 v87, 0xbfb8aa3b, v87
	v_cvt_pk_u8_f32 v96, v97, 2, v96
	v_fma_f32 v97, v99, s29, -0.5
	v_exp_f32_e32 v95, v95
	v_exp_f32_e32 v91, v91
	v_exp_f32_e32 v87, v87
	v_cvt_pk_u8_f32 v92, v97, 3, v96
	v_add_f32_e32 v96, 1.0, v98
	v_add_f32_e32 v88, 1.0, v88
	v_add_f32_e32 v84, 1.0, v84
	v_rcp_f32_e32 v96, v96
	v_add_f32_e32 v93, 1.0, v93
	v_rcp_f32_e32 v88, v88
	v_add_f32_e32 v89, 1.0, v89
	v_rcp_f32_e32 v84, v84
	v_add_f32_e32 v85, 1.0, v85
	v_rcp_f32_e32 v93, v93
	v_add_f32_e32 v94, 1.0, v94
	v_rcp_f32_e32 v89, v89
	v_add_f32_e32 v90, 1.0, v90
	v_rcp_f32_e32 v85, v85
	v_add_f32_e32 v86, 1.0, v86
	v_rcp_f32_e32 v94, v94
	v_add_f32_e32 v95, 1.0, v95
	v_rcp_f32_e32 v90, v90
	v_add_f32_e32 v91, 1.0, v91
	v_rcp_f32_e32 v86, v86
	v_add_f32_e32 v87, 1.0, v87
	v_rcp_f32_e32 v95, v95
	v_rcp_f32_e32 v91, v91
	v_rcp_f32_e32 v87, v87
	v_fma_f32 v96, v96, s29, -0.5
	v_fma_f32 v88, v88, s29, -0.5
	v_fma_f32 v84, v84, s29, -0.5
	v_cvt_pk_u8_f32 v96, v96, 0, 0
	v_fma_f32 v93, v93, s29, -0.5
	v_cvt_pk_u8_f32 v88, v88, 0, 0
	v_fma_f32 v89, v89, s29, -0.5
	v_cvt_pk_u8_f32 v84, v84, 0, 0
	v_fma_f32 v85, v85, s29, -0.5
	v_cvt_pk_u8_f32 v93, v93, 1, v96
	v_fma_f32 v94, v94, s29, -0.5
	v_cvt_pk_u8_f32 v88, v89, 1, v88
	v_fma_f32 v89, v90, s29, -0.5
	v_cvt_pk_u8_f32 v84, v85, 1, v84
	v_fma_f32 v85, v86, s29, -0.5
	v_cvt_pk_u8_f32 v93, v94, 2, v93
	v_fma_f32 v94, v95, s29, -0.5
	v_cvt_pk_u8_f32 v88, v89, 2, v88
	v_fma_f32 v89, v91, s29, -0.5
	v_cvt_pk_u8_f32 v84, v85, 2, v84
	v_fma_f32 v85, v87, s29, -0.5
	v_cvt_pk_u8_f32 v93, v94, 3, v93
	v_cvt_pk_u8_f32 v94, v89, 3, v88
	v_cvt_pk_u8_f32 v95, v85, 3, v84
	v_mad_u64_u32 v[84:85], s[4:5], v223, s20, v[2:3]
	global_store_dwordx4 v84, v[92:95], s[72:73]
	v_mul_f32_e32 v80, 0xbfb8aa3b, v80
	v_exp_f32_e32 v80, v80
	v_mul_f32_e32 v81, 0xbfb8aa3b, v81
	v_exp_f32_e32 v81, v81
	v_mul_f32_e32 v82, 0xbfb8aa3b, v82
	v_exp_f32_e32 v82, v82
	v_add_f32_e32 v80, 1.0, v80
	v_rcp_f32_e32 v80, v80
	v_add_f32_e32 v81, 1.0, v81
	v_mul_f32_e32 v83, 0xbfb8aa3b, v83
	v_rcp_f32_e32 v81, v81
	v_add_f32_e32 v82, 1.0, v82
	v_exp_f32_e32 v83, v83
	v_rcp_f32_e32 v82, v82
	v_fma_f32 v80, v80, s29, -0.5
	v_cvt_pk_u8_f32 v80, v80, 0, 0
	v_fma_f32 v81, v81, s29, -0.5
	v_mul_f32_e32 v76, 0xbfb8aa3b, v76
	v_add_f32_e32 v83, 1.0, v83
	v_cvt_pk_u8_f32 v80, v81, 1, v80
	v_fma_f32 v81, v82, s29, -0.5
	v_exp_f32_e32 v82, v76
	v_mov_b32_e32 v76, v77
	v_rcp_f32_e32 v83, v83
	v_mul_f32_e32 v72, 0xbfb8aa3b, v72
	v_mul_f32_e32 v68, 0xbfb8aa3b, v68
	v_mul_f32_e32 v76, 0xbfb8aa3b, v76
	v_exp_f32_e32 v72, v72
	v_mul_f32_e32 v73, 0xbfb8aa3b, v73
	v_exp_f32_e32 v68, v68
	v_mul_f32_e32 v69, 0xbfb8aa3b, v69
	v_exp_f32_e32 v77, v76
	v_mul_f32_e32 v78, 0xbfb8aa3b, v78
	v_exp_f32_e32 v73, v73
	v_mul_f32_e32 v74, 0xbfb8aa3b, v74
	v_exp_f32_e32 v69, v69
	v_mul_f32_e32 v70, 0xbfb8aa3b, v70
	v_exp_f32_e32 v78, v78
	v_mul_f32_e32 v79, 0xbfb8aa3b, v79
	v_exp_f32_e32 v74, v74
	v_mul_f32_e32 v75, 0xbfb8aa3b, v75
	v_exp_f32_e32 v70, v70
	v_mul_f32_e32 v71, 0xbfb8aa3b, v71
	v_cvt_pk_u8_f32 v80, v81, 2, v80
	v_fma_f32 v81, v83, s29, -0.5
	v_exp_f32_e32 v79, v79
	v_exp_f32_e32 v75, v75
	v_exp_f32_e32 v71, v71
	v_cvt_pk_u8_f32 v76, v81, 3, v80
	v_add_f32_e32 v80, 1.0, v82
	v_add_f32_e32 v72, 1.0, v72
	v_add_f32_e32 v68, 1.0, v68
	v_rcp_f32_e32 v80, v80
	v_add_f32_e32 v77, 1.0, v77
	v_rcp_f32_e32 v72, v72
	v_add_f32_e32 v73, 1.0, v73
	v_rcp_f32_e32 v68, v68
	v_add_f32_e32 v69, 1.0, v69
	v_rcp_f32_e32 v77, v77
	v_add_f32_e32 v78, 1.0, v78
	v_rcp_f32_e32 v73, v73
	v_add_f32_e32 v74, 1.0, v74
	v_rcp_f32_e32 v69, v69
	v_add_f32_e32 v70, 1.0, v70
	v_rcp_f32_e32 v78, v78
	v_add_f32_e32 v79, 1.0, v79
	v_rcp_f32_e32 v74, v74
	v_add_f32_e32 v75, 1.0, v75
	v_rcp_f32_e32 v70, v70
	v_add_f32_e32 v71, 1.0, v71
	v_rcp_f32_e32 v79, v79
	v_rcp_f32_e32 v75, v75
	v_rcp_f32_e32 v71, v71
	v_fma_f32 v80, v80, s29, -0.5
	v_fma_f32 v72, v72, s29, -0.5
	v_fma_f32 v68, v68, s29, -0.5
	v_cvt_pk_u8_f32 v80, v80, 0, 0
	v_fma_f32 v77, v77, s29, -0.5
	v_cvt_pk_u8_f32 v72, v72, 0, 0
	v_fma_f32 v73, v73, s29, -0.5
	v_cvt_pk_u8_f32 v68, v68, 0, 0
	v_fma_f32 v69, v69, s29, -0.5
	v_cvt_pk_u8_f32 v77, v77, 1, v80
	v_fma_f32 v78, v78, s29, -0.5
	v_cvt_pk_u8_f32 v72, v73, 1, v72
	v_fma_f32 v73, v74, s29, -0.5
	v_cvt_pk_u8_f32 v68, v69, 1, v68
	v_fma_f32 v69, v70, s29, -0.5
	v_cvt_pk_u8_f32 v77, v78, 2, v77
	v_fma_f32 v78, v79, s29, -0.5
	v_cvt_pk_u8_f32 v72, v73, 2, v72
	v_fma_f32 v73, v75, s29, -0.5
	v_cvt_pk_u8_f32 v68, v69, 2, v68
	v_fma_f32 v69, v71, s29, -0.5
	v_cvt_pk_u8_f32 v77, v78, 3, v77
	v_cvt_pk_u8_f32 v78, v73, 3, v72
	v_cvt_pk_u8_f32 v79, v69, 3, v68
	v_mad_u64_u32 v[68:69], s[4:5], v222, s20, v[2:3]
	global_store_dwordx4 v68, v[76:79], s[72:73]
	v_mul_f32_e32 v64, 0xbfb8aa3b, v64
	v_exp_f32_e32 v64, v64
	v_mul_f32_e32 v65, 0xbfb8aa3b, v65
	v_exp_f32_e32 v65, v65
	v_mul_f32_e32 v66, 0xbfb8aa3b, v66
	v_exp_f32_e32 v66, v66
	v_add_f32_e32 v64, 1.0, v64
	v_rcp_f32_e32 v64, v64
	v_add_f32_e32 v65, 1.0, v65
	v_mul_f32_e32 v67, 0xbfb8aa3b, v67
	v_rcp_f32_e32 v65, v65
	v_add_f32_e32 v66, 1.0, v66
	v_exp_f32_e32 v67, v67
	v_rcp_f32_e32 v66, v66
	v_fma_f32 v64, v64, s29, -0.5
	v_cvt_pk_u8_f32 v64, v64, 0, 0
	v_fma_f32 v65, v65, s29, -0.5
	v_mul_f32_e32 v60, 0xbfb8aa3b, v60
	v_add_f32_e32 v67, 1.0, v67
	v_cvt_pk_u8_f32 v64, v65, 1, v64
	v_fma_f32 v65, v66, s29, -0.5
	v_exp_f32_e32 v66, v60
	v_mov_b32_e32 v60, v61
	v_rcp_f32_e32 v67, v67
	v_mul_f32_e32 v56, 0xbfb8aa3b, v56
	v_mul_f32_e32 v52, 0xbfb8aa3b, v52
	v_mul_f32_e32 v60, 0xbfb8aa3b, v60
	v_exp_f32_e32 v56, v56
	v_mul_f32_e32 v57, 0xbfb8aa3b, v57
	v_exp_f32_e32 v52, v52
	v_mul_f32_e32 v53, 0xbfb8aa3b, v53
	v_exp_f32_e32 v61, v60
	v_mul_f32_e32 v62, 0xbfb8aa3b, v62
	v_exp_f32_e32 v57, v57
	v_mul_f32_e32 v58, 0xbfb8aa3b, v58
	v_exp_f32_e32 v53, v53
	v_mul_f32_e32 v54, 0xbfb8aa3b, v54
	v_exp_f32_e32 v62, v62
	v_mul_f32_e32 v63, 0xbfb8aa3b, v63
	v_exp_f32_e32 v58, v58
	v_mul_f32_e32 v59, 0xbfb8aa3b, v59
	v_exp_f32_e32 v54, v54
	v_mul_f32_e32 v55, 0xbfb8aa3b, v55
	v_cvt_pk_u8_f32 v64, v65, 2, v64
	v_fma_f32 v65, v67, s29, -0.5
	v_exp_f32_e32 v63, v63
	v_exp_f32_e32 v59, v59
	v_exp_f32_e32 v55, v55
	v_cvt_pk_u8_f32 v60, v65, 3, v64
	v_add_f32_e32 v64, 1.0, v66
	v_add_f32_e32 v56, 1.0, v56
	v_add_f32_e32 v52, 1.0, v52
	v_rcp_f32_e32 v64, v64
	v_add_f32_e32 v61, 1.0, v61
	v_rcp_f32_e32 v56, v56
	v_add_f32_e32 v57, 1.0, v57
	v_rcp_f32_e32 v52, v52
	v_add_f32_e32 v53, 1.0, v53
	v_rcp_f32_e32 v61, v61
	v_add_f32_e32 v62, 1.0, v62
	v_rcp_f32_e32 v57, v57
	v_add_f32_e32 v58, 1.0, v58
	v_rcp_f32_e32 v53, v53
	v_add_f32_e32 v54, 1.0, v54
	v_rcp_f32_e32 v62, v62
	v_add_f32_e32 v63, 1.0, v63
	v_rcp_f32_e32 v58, v58
	v_add_f32_e32 v59, 1.0, v59
	v_rcp_f32_e32 v54, v54
	v_add_f32_e32 v55, 1.0, v55
	v_rcp_f32_e32 v63, v63
	v_rcp_f32_e32 v59, v59
	v_rcp_f32_e32 v55, v55
	v_fma_f32 v64, v64, s29, -0.5
	v_fma_f32 v56, v56, s29, -0.5
	v_fma_f32 v52, v52, s29, -0.5
	v_cvt_pk_u8_f32 v64, v64, 0, 0
	v_fma_f32 v61, v61, s29, -0.5
	v_cvt_pk_u8_f32 v56, v56, 0, 0
	v_fma_f32 v57, v57, s29, -0.5
	v_cvt_pk_u8_f32 v52, v52, 0, 0
	v_fma_f32 v53, v53, s29, -0.5
	v_cvt_pk_u8_f32 v61, v61, 1, v64
	v_fma_f32 v62, v62, s29, -0.5
	v_cvt_pk_u8_f32 v56, v57, 1, v56
	v_fma_f32 v57, v58, s29, -0.5
	v_cvt_pk_u8_f32 v52, v53, 1, v52
	v_fma_f32 v53, v54, s29, -0.5
	v_cvt_pk_u8_f32 v61, v62, 2, v61
	v_fma_f32 v62, v63, s29, -0.5
	v_cvt_pk_u8_f32 v56, v57, 2, v56
	v_fma_f32 v57, v59, s29, -0.5
	v_cvt_pk_u8_f32 v52, v53, 2, v52
	v_fma_f32 v53, v55, s29, -0.5
	v_cvt_pk_u8_f32 v61, v62, 3, v61
	v_cvt_pk_u8_f32 v62, v57, 3, v56
	v_cvt_pk_u8_f32 v63, v53, 3, v52
	v_mad_u64_u32 v[52:53], s[4:5], v221, s20, v[2:3]
	global_store_dwordx4 v52, v[60:63], s[72:73]
	v_mul_f32_e32 v48, 0xbfb8aa3b, v48
	v_exp_f32_e32 v48, v48
	v_mul_f32_e32 v49, 0xbfb8aa3b, v49
	v_exp_f32_e32 v49, v49
	v_mul_f32_e32 v50, 0xbfb8aa3b, v50
	v_exp_f32_e32 v50, v50
	v_add_f32_e32 v48, 1.0, v48
	v_rcp_f32_e32 v48, v48
	v_add_f32_e32 v49, 1.0, v49
	v_mul_f32_e32 v51, 0xbfb8aa3b, v51
	v_rcp_f32_e32 v49, v49
	v_add_f32_e32 v50, 1.0, v50
	v_exp_f32_e32 v51, v51
	v_rcp_f32_e32 v50, v50
	v_fma_f32 v48, v48, s29, -0.5
	v_cvt_pk_u8_f32 v48, v48, 0, 0
	v_fma_f32 v49, v49, s29, -0.5
	v_mul_f32_e32 v44, 0xbfb8aa3b, v44
	v_add_f32_e32 v51, 1.0, v51
	v_cvt_pk_u8_f32 v48, v49, 1, v48
	v_fma_f32 v49, v50, s29, -0.5
	v_exp_f32_e32 v50, v44
	v_mov_b32_e32 v44, v45
	v_rcp_f32_e32 v51, v51
	v_mul_f32_e32 v40, 0xbfb8aa3b, v40
	v_mul_f32_e32 v36, 0xbfb8aa3b, v36
	v_mul_f32_e32 v44, 0xbfb8aa3b, v44
	v_exp_f32_e32 v40, v40
	v_mul_f32_e32 v41, 0xbfb8aa3b, v41
	v_exp_f32_e32 v36, v36
	v_mul_f32_e32 v37, 0xbfb8aa3b, v37
	v_exp_f32_e32 v45, v44
	v_mul_f32_e32 v46, 0xbfb8aa3b, v46
	v_exp_f32_e32 v41, v41
	v_mul_f32_e32 v42, 0xbfb8aa3b, v42
	v_exp_f32_e32 v37, v37
	v_mul_f32_e32 v38, 0xbfb8aa3b, v38
	v_exp_f32_e32 v46, v46
	v_mul_f32_e32 v47, 0xbfb8aa3b, v47
	v_exp_f32_e32 v42, v42
	v_mul_f32_e32 v43, 0xbfb8aa3b, v43
	v_exp_f32_e32 v38, v38
	v_mul_f32_e32 v39, 0xbfb8aa3b, v39
	v_cvt_pk_u8_f32 v48, v49, 2, v48
	v_fma_f32 v49, v51, s29, -0.5
	v_exp_f32_e32 v47, v47
	v_exp_f32_e32 v43, v43
	v_exp_f32_e32 v39, v39
	v_cvt_pk_u8_f32 v44, v49, 3, v48
	v_add_f32_e32 v48, 1.0, v50
	v_add_f32_e32 v40, 1.0, v40
	v_add_f32_e32 v36, 1.0, v36
	v_rcp_f32_e32 v48, v48
	v_add_f32_e32 v45, 1.0, v45
	v_rcp_f32_e32 v40, v40
	v_add_f32_e32 v41, 1.0, v41
	v_rcp_f32_e32 v36, v36
	v_add_f32_e32 v37, 1.0, v37
	v_rcp_f32_e32 v45, v45
	v_add_f32_e32 v46, 1.0, v46
	v_rcp_f32_e32 v41, v41
	v_add_f32_e32 v42, 1.0, v42
	v_rcp_f32_e32 v37, v37
	v_add_f32_e32 v38, 1.0, v38
	v_rcp_f32_e32 v46, v46
	v_add_f32_e32 v47, 1.0, v47
	v_rcp_f32_e32 v42, v42
	v_add_f32_e32 v43, 1.0, v43
	v_rcp_f32_e32 v38, v38
	v_add_f32_e32 v39, 1.0, v39
	v_rcp_f32_e32 v47, v47
	v_rcp_f32_e32 v43, v43
	v_rcp_f32_e32 v39, v39
	v_fma_f32 v48, v48, s29, -0.5
	v_fma_f32 v40, v40, s29, -0.5
	v_fma_f32 v36, v36, s29, -0.5
	v_cvt_pk_u8_f32 v48, v48, 0, 0
	v_fma_f32 v45, v45, s29, -0.5
	v_cvt_pk_u8_f32 v40, v40, 0, 0
	v_fma_f32 v41, v41, s29, -0.5
	v_cvt_pk_u8_f32 v36, v36, 0, 0
	v_fma_f32 v37, v37, s29, -0.5
	v_cvt_pk_u8_f32 v45, v45, 1, v48
	v_fma_f32 v46, v46, s29, -0.5
	v_cvt_pk_u8_f32 v40, v41, 1, v40
	v_fma_f32 v41, v42, s29, -0.5
	v_cvt_pk_u8_f32 v36, v37, 1, v36
	v_fma_f32 v37, v38, s29, -0.5
	v_cvt_pk_u8_f32 v45, v46, 2, v45
	v_fma_f32 v46, v47, s29, -0.5
	v_cvt_pk_u8_f32 v40, v41, 2, v40
	v_fma_f32 v41, v43, s29, -0.5
	v_cvt_pk_u8_f32 v36, v37, 2, v36
	v_fma_f32 v37, v39, s29, -0.5
	v_cvt_pk_u8_f32 v45, v46, 3, v45
	v_cvt_pk_u8_f32 v46, v41, 3, v40
	v_cvt_pk_u8_f32 v47, v37, 3, v36
	v_mad_u64_u32 v[36:37], s[4:5], v220, s20, v[2:3]
	global_store_dwordx4 v36, v[44:47], s[72:73]
	v_mul_f32_e32 v32, 0xbfb8aa3b, v32
	v_exp_f32_e32 v32, v32
	v_mul_f32_e32 v33, 0xbfb8aa3b, v33
	v_exp_f32_e32 v33, v33
	v_mul_f32_e32 v34, 0xbfb8aa3b, v34
	v_exp_f32_e32 v34, v34
	v_add_f32_e32 v32, 1.0, v32
	v_rcp_f32_e32 v32, v32
	v_add_f32_e32 v33, 1.0, v33
	v_mul_f32_e32 v35, 0xbfb8aa3b, v35
	v_rcp_f32_e32 v33, v33
	v_add_f32_e32 v34, 1.0, v34
	v_exp_f32_e32 v35, v35
	v_rcp_f32_e32 v34, v34
	v_fma_f32 v32, v32, s29, -0.5
	v_cvt_pk_u8_f32 v32, v32, 0, 0
	v_fma_f32 v33, v33, s29, -0.5
	v_mul_f32_e32 v28, 0xbfb8aa3b, v28
	v_add_f32_e32 v35, 1.0, v35
	v_cvt_pk_u8_f32 v32, v33, 1, v32
	v_fma_f32 v33, v34, s29, -0.5
	v_exp_f32_e32 v34, v28
	v_mov_b32_e32 v28, v29
	v_rcp_f32_e32 v35, v35
	v_mul_f32_e32 v24, 0xbfb8aa3b, v24
	v_mul_f32_e32 v20, 0xbfb8aa3b, v20
	v_mul_f32_e32 v28, 0xbfb8aa3b, v28
	v_exp_f32_e32 v24, v24
	v_mul_f32_e32 v25, 0xbfb8aa3b, v25
	v_exp_f32_e32 v20, v20
	v_mul_f32_e32 v21, 0xbfb8aa3b, v21
	v_exp_f32_e32 v29, v28
	v_mul_f32_e32 v30, 0xbfb8aa3b, v30
	v_exp_f32_e32 v25, v25
	v_mul_f32_e32 v26, 0xbfb8aa3b, v26
	v_exp_f32_e32 v21, v21
	v_mul_f32_e32 v22, 0xbfb8aa3b, v22
	v_exp_f32_e32 v30, v30
	v_mul_f32_e32 v31, 0xbfb8aa3b, v31
	v_exp_f32_e32 v26, v26
	v_mul_f32_e32 v27, 0xbfb8aa3b, v27
	v_exp_f32_e32 v22, v22
	v_mul_f32_e32 v23, 0xbfb8aa3b, v23
	v_cvt_pk_u8_f32 v32, v33, 2, v32
	v_fma_f32 v33, v35, s29, -0.5
	v_exp_f32_e32 v31, v31
	v_exp_f32_e32 v27, v27
	v_exp_f32_e32 v23, v23
	v_cvt_pk_u8_f32 v28, v33, 3, v32
	v_add_f32_e32 v32, 1.0, v34
	v_add_f32_e32 v24, 1.0, v24
	v_add_f32_e32 v20, 1.0, v20
	v_rcp_f32_e32 v32, v32
	v_add_f32_e32 v29, 1.0, v29
	v_rcp_f32_e32 v24, v24
	v_add_f32_e32 v25, 1.0, v25
	v_rcp_f32_e32 v20, v20
	v_add_f32_e32 v21, 1.0, v21
	v_rcp_f32_e32 v29, v29
	v_add_f32_e32 v30, 1.0, v30
	v_rcp_f32_e32 v25, v25
	v_add_f32_e32 v26, 1.0, v26
	v_rcp_f32_e32 v21, v21
	v_add_f32_e32 v22, 1.0, v22
	v_rcp_f32_e32 v30, v30
	v_add_f32_e32 v31, 1.0, v31
	v_rcp_f32_e32 v26, v26
	v_add_f32_e32 v27, 1.0, v27
	v_rcp_f32_e32 v22, v22
	v_add_f32_e32 v23, 1.0, v23
	v_rcp_f32_e32 v31, v31
	v_rcp_f32_e32 v27, v27
	v_rcp_f32_e32 v23, v23
	v_fma_f32 v32, v32, s29, -0.5
	v_fma_f32 v24, v24, s29, -0.5
	v_fma_f32 v20, v20, s29, -0.5
	v_cvt_pk_u8_f32 v32, v32, 0, 0
	v_fma_f32 v29, v29, s29, -0.5
	v_cvt_pk_u8_f32 v24, v24, 0, 0
	v_fma_f32 v25, v25, s29, -0.5
	v_cvt_pk_u8_f32 v20, v20, 0, 0
	v_fma_f32 v21, v21, s29, -0.5
	v_cvt_pk_u8_f32 v29, v29, 1, v32
	v_fma_f32 v30, v30, s29, -0.5
	v_cvt_pk_u8_f32 v24, v25, 1, v24
	v_fma_f32 v25, v26, s29, -0.5
	v_cvt_pk_u8_f32 v20, v21, 1, v20
	v_fma_f32 v21, v22, s29, -0.5
	v_cvt_pk_u8_f32 v29, v30, 2, v29
	v_fma_f32 v30, v31, s29, -0.5
	v_cvt_pk_u8_f32 v24, v25, 2, v24
	v_fma_f32 v25, v27, s29, -0.5
	v_cvt_pk_u8_f32 v20, v21, 2, v20
	v_fma_f32 v21, v23, s29, -0.5
	v_cvt_pk_u8_f32 v29, v30, 3, v29
	v_cvt_pk_u8_f32 v30, v25, 3, v24
	v_cvt_pk_u8_f32 v31, v21, 3, v20
	v_mad_u64_u32 v[20:21], s[4:5], v195, s20, v[2:3]
	global_store_dwordx4 v20, v[28:31], s[72:73]
	v_mul_f32_e32 v16, 0xbfb8aa3b, v16
	v_exp_f32_e32 v16, v16
	v_mul_f32_e32 v17, 0xbfb8aa3b, v17
	v_exp_f32_e32 v17, v17
	v_mul_f32_e32 v18, 0xbfb8aa3b, v18
	v_exp_f32_e32 v18, v18
	v_add_f32_e32 v16, 1.0, v16
	v_rcp_f32_e32 v16, v16
	v_add_f32_e32 v17, 1.0, v17
	v_mul_f32_e32 v19, 0xbfb8aa3b, v19
	v_rcp_f32_e32 v17, v17
	v_add_f32_e32 v18, 1.0, v18
	v_exp_f32_e32 v19, v19
	v_rcp_f32_e32 v18, v18
	v_fma_f32 v16, v16, s29, -0.5
	v_cvt_pk_u8_f32 v16, v16, 0, 0
	v_fma_f32 v17, v17, s29, -0.5
	v_mul_f32_e32 v12, 0xbfb8aa3b, v12
	v_add_f32_e32 v19, 1.0, v19
	v_cvt_pk_u8_f32 v16, v17, 1, v16
	v_fma_f32 v17, v18, s29, -0.5
	v_exp_f32_e32 v18, v12
	v_mov_b32_e32 v12, v13
	v_rcp_f32_e32 v19, v19
	v_mul_f32_e32 v8, 0xbfb8aa3b, v8
	v_mul_f32_e32 v4, 0xbfb8aa3b, v4
	v_mul_f32_e32 v12, 0xbfb8aa3b, v12
	v_exp_f32_e32 v8, v8
	v_mul_f32_e32 v9, 0xbfb8aa3b, v9
	v_exp_f32_e32 v4, v4
	v_mul_f32_e32 v5, 0xbfb8aa3b, v5
	v_exp_f32_e32 v13, v12
	v_mul_f32_e32 v14, 0xbfb8aa3b, v14
	v_exp_f32_e32 v9, v9
	v_mul_f32_e32 v10, 0xbfb8aa3b, v10
	v_exp_f32_e32 v5, v5
	v_mul_f32_e32 v6, 0xbfb8aa3b, v6
	v_exp_f32_e32 v14, v14
	v_mul_f32_e32 v15, 0xbfb8aa3b, v15
	v_exp_f32_e32 v10, v10
	v_mul_f32_e32 v11, 0xbfb8aa3b, v11
	v_exp_f32_e32 v6, v6
	v_mul_f32_e32 v7, 0xbfb8aa3b, v7
	v_cvt_pk_u8_f32 v16, v17, 2, v16
	v_fma_f32 v17, v19, s29, -0.5
	v_exp_f32_e32 v15, v15
	v_exp_f32_e32 v11, v11
	v_exp_f32_e32 v7, v7
	v_cvt_pk_u8_f32 v12, v17, 3, v16
	v_add_f32_e32 v16, 1.0, v18
	v_add_f32_e32 v8, 1.0, v8
	v_add_f32_e32 v4, 1.0, v4
	v_rcp_f32_e32 v16, v16
	v_add_f32_e32 v13, 1.0, v13
	v_rcp_f32_e32 v8, v8
	v_add_f32_e32 v9, 1.0, v9
	v_rcp_f32_e32 v4, v4
	v_add_f32_e32 v5, 1.0, v5
	v_rcp_f32_e32 v13, v13
	v_add_f32_e32 v14, 1.0, v14
	v_rcp_f32_e32 v9, v9
	v_add_f32_e32 v10, 1.0, v10
	v_rcp_f32_e32 v5, v5
	v_add_f32_e32 v6, 1.0, v6
	v_rcp_f32_e32 v14, v14
	v_add_f32_e32 v15, 1.0, v15
	v_rcp_f32_e32 v10, v10
	v_add_f32_e32 v11, 1.0, v11
	v_rcp_f32_e32 v6, v6
	v_add_f32_e32 v7, 1.0, v7
	v_rcp_f32_e32 v15, v15
	v_rcp_f32_e32 v11, v11
	v_rcp_f32_e32 v7, v7
	v_fma_f32 v16, v16, s29, -0.5
	v_fma_f32 v8, v8, s29, -0.5
	v_fma_f32 v4, v4, s29, -0.5
	v_cvt_pk_u8_f32 v16, v16, 0, 0
	v_fma_f32 v13, v13, s29, -0.5
	v_cvt_pk_u8_f32 v8, v8, 0, 0
	v_fma_f32 v9, v9, s29, -0.5
	v_cvt_pk_u8_f32 v4, v4, 0, 0
	v_fma_f32 v5, v5, s29, -0.5
	v_cvt_pk_u8_f32 v13, v13, 1, v16
	v_fma_f32 v14, v14, s29, -0.5
	v_cvt_pk_u8_f32 v8, v9, 1, v8
	v_fma_f32 v9, v10, s29, -0.5
	v_cvt_pk_u8_f32 v4, v5, 1, v4
	v_fma_f32 v5, v6, s29, -0.5
	v_cvt_pk_u8_f32 v13, v14, 2, v13
	v_fma_f32 v14, v15, s29, -0.5
	v_cvt_pk_u8_f32 v8, v9, 2, v8
	v_fma_f32 v9, v11, s29, -0.5
	v_cvt_pk_u8_f32 v4, v5, 2, v4
	v_fma_f32 v5, v7, s29, -0.5
	v_cvt_pk_u8_f32 v13, v14, 3, v13
	v_cvt_pk_u8_f32 v14, v9, 3, v8
	v_cvt_pk_u8_f32 v15, v5, 3, v4
	v_mad_u64_u32 v[4:5], s[4:5], v194, s20, v[2:3]
	global_store_dwordx4 v4, v[12:15], s[72:73]
	s_andn2_b64 vcc, exec, s[74:75]
	s_mov_b64 s[4:5], -1
	s_cbranch_vccnz .LBB0_1263
	s_branch .LBB0_1539
